# diff/SWA loops: 4 instead of 8 K/V fragment buffers (shorter LDS burst after QK)
# speedup vs baseline: 1.0025x; 1.0017x over previous
.Latt_swa_nomasktest:
	ds_read_b128 v[210:213], v208 offset:0
	ds_read_b128 v[214:217], v208 offset:4608
	ds_read_b128 v[218:221], v208 offset:32
	ds_read_b128 v[222:225], v208 offset:4640
	s_waitcnt lgkmcnt(3)
	v_mfma_f32_32x32x16_bf16 v[64:79], v[210:213], v[96:99], v[154:169]
	ds_read_b128 v[210:213], v208 offset:64
	s_waitcnt lgkmcnt(3)
	v_mfma_f32_32x32x16_bf16 v[32:47], v[214:217], v[96:99], v[154:169]
	ds_read_b128 v[214:217], v208 offset:4672
	s_waitcnt lgkmcnt(3)
	v_mfma_f32_32x32x16_bf16 v[64:79], v[218:221], v[100:103], v[64:79]
	ds_read_b128 v[218:221], v208 offset:96
	s_waitcnt lgkmcnt(3)
	v_mfma_f32_32x32x16_bf16 v[32:47], v[222:225], v[100:103], v[32:47]
	ds_read_b128 v[222:225], v208 offset:4704
	s_waitcnt lgkmcnt(3)
	v_mfma_f32_32x32x16_bf16 v[64:79], v[210:213], v[104:107], v[64:79]
	s_waitcnt lgkmcnt(2)
	v_mfma_f32_32x32x16_bf16 v[32:47], v[214:217], v[104:107], v[32:47]
	s_waitcnt lgkmcnt(1)
	v_mfma_f32_32x32x16_bf16 v[64:79], v[218:221], v[108:111], v[64:79]
	s_waitcnt lgkmcnt(0)
	v_mfma_f32_32x32x16_bf16 v[32:47], v[222:225], v[108:111], v[32:47]
	ds_read_b128 v[210:213], v209 offset:27648
	ds_read_b128 v[214:217], v209 offset:32256
	ds_read_b128 v[218:221], v209 offset:27680
	ds_read_b128 v[222:225], v209 offset:32288
	s_nop 6
	s_nop 0
	s_cmp_lt_u32 s47, 4
	s_cbranch_scc1 .Latt_swa_nomask
	s_cmp_eq_u64 s[36:37], exec
	s_cbranch_scc1 .Latt_swa_nomask
	v_add_u32_e32 v48, s43, v127
	v_add_u32_e32 v49, 0xfffffe7f, v48
	v_cmp_lt_u32_e32 vcc, s50, v49
	v_add_u32_e32 v49, 0xfffffe9f, v48
	s_nop 0
	v_cndmask_b32_e32 v64, v233, v64, vcc
	v_cmp_lt_u32_e32 vcc, s50, v49
	v_add_u32_e32 v49, 0xfffffe80, v48
	s_nop 0
	v_cndmask_b32_e32 v32, v233, v32, vcc
	v_cmp_lt_u32_e32 vcc, s50, v49
	v_add_u32_e32 v49, 0xfffffea0, v48
	s_nop 0
	v_cndmask_b32_e32 v65, v233, v65, vcc
	v_cmp_lt_u32_e32 vcc, s50, v49
	v_add_u32_e32 v49, 0xfffffe81, v48
	s_nop 0
	v_cndmask_b32_e32 v33, v233, v33, vcc
	v_cmp_lt_u32_e32 vcc, s50, v49
	v_add_u32_e32 v49, 0xfffffea1, v48
	s_nop 0
	v_cndmask_b32_e32 v66, v233, v66, vcc
	v_cmp_lt_u32_e32 vcc, s50, v49
	v_add_u32_e32 v49, 0xfffffe82, v48
	s_nop 0
	v_cndmask_b32_e32 v34, v233, v34, vcc
	v_cmp_lt_u32_e32 vcc, s50, v49
	v_add_u32_e32 v49, 0xfffffea2, v48
	s_nop 0
	v_cndmask_b32_e32 v67, v233, v67, vcc
	v_cmp_lt_u32_e32 vcc, s50, v49
	v_add_u32_e32 v49, 0xfffffe83, v48
	s_nop 0
	v_cndmask_b32_e32 v35, v233, v35, vcc
	v_cmp_lt_u32_e32 vcc, s50, v49
	v_add_u32_e32 v49, 0xfffffea3, v48
	s_nop 0
	v_cndmask_b32_e32 v68, v233, v68, vcc
	v_cmp_lt_u32_e32 vcc, s50, v49
	v_add_u32_e32 v49, 0xfffffe84, v48
	s_nop 0
	v_cndmask_b32_e32 v36, v233, v36, vcc
	v_cmp_lt_u32_e32 vcc, s50, v49
	v_add_u32_e32 v49, 0xfffffea4, v48
	s_nop 0
	v_cndmask_b32_e32 v69, v233, v69, vcc
	v_cmp_lt_u32_e32 vcc, s50, v49
	v_add_u32_e32 v49, 0xfffffe85, v48
	s_nop 0
	v_cndmask_b32_e32 v37, v233, v37, vcc
	v_cmp_lt_u32_e32 vcc, s50, v49
	v_add_u32_e32 v49, 0xfffffea5, v48
	s_nop 0
	v_cndmask_b32_e32 v70, v233, v70, vcc
	v_cmp_lt_u32_e32 vcc, s50, v49
	v_add_u32_e32 v49, 0xfffffe86, v48
	s_nop 0
	v_cndmask_b32_e32 v38, v233, v38, vcc
	v_cmp_lt_u32_e32 vcc, s50, v49
	v_add_u32_e32 v49, 0xfffffea6, v48
	s_nop 0
	v_cndmask_b32_e32 v71, v233, v71, vcc
	v_cmp_lt_u32_e32 vcc, s50, v49
	v_add_u32_e32 v49, 0xfffffe8f, v48
	s_nop 0
	v_cndmask_b32_e32 v39, v233, v39, vcc
	v_cmp_lt_u32_e32 vcc, s50, v49
	v_add_u32_e32 v49, 0xfffffeaf, v48
	s_nop 0
	v_cndmask_b32_e32 v72, v233, v72, vcc
	v_cmp_lt_u32_e32 vcc, s50, v49
	v_add_u32_e32 v49, 0xfffffe90, v48
	s_nop 0
	v_cndmask_b32_e32 v40, v233, v40, vcc
	v_cmp_lt_u32_e32 vcc, s50, v49
	v_add_u32_e32 v49, 0xfffffeb0, v48
	s_nop 0
	v_cndmask_b32_e32 v73, v233, v73, vcc
	v_cmp_lt_u32_e32 vcc, s50, v49
	v_add_u32_e32 v49, 0xfffffe91, v48
	s_nop 0
	v_cndmask_b32_e32 v41, v233, v41, vcc
	v_cmp_lt_u32_e32 vcc, s50, v49
	v_add_u32_e32 v49, 0xfffffeb1, v48
	s_nop 0
	v_cndmask_b32_e32 v74, v233, v74, vcc
	v_cmp_lt_u32_e32 vcc, s50, v49
	v_add_u32_e32 v49, 0xfffffe92, v48
	s_nop 0
	v_cndmask_b32_e32 v42, v233, v42, vcc
	v_cmp_lt_u32_e32 vcc, s50, v49
	v_add_u32_e32 v49, 0xfffffeb2, v48
	s_nop 0
	v_cndmask_b32_e32 v75, v233, v75, vcc
	v_cmp_lt_u32_e32 vcc, s50, v49
	v_add_u32_e32 v49, 0xfffffe93, v48
	s_nop 0
	v_cndmask_b32_e32 v43, v233, v43, vcc
	v_cmp_lt_u32_e32 vcc, s50, v49
	v_add_u32_e32 v49, 0xfffffeb3, v48
	s_nop 0
	v_cndmask_b32_e32 v76, v233, v76, vcc
	v_cmp_lt_u32_e32 vcc, s50, v49
	v_add_u32_e32 v49, 0xfffffe94, v48
	s_nop 0
	v_cndmask_b32_e32 v44, v233, v44, vcc
	v_cmp_lt_u32_e32 vcc, s50, v49
	v_add_u32_e32 v49, 0xfffffeb4, v48
	s_nop 0
	v_cndmask_b32_e32 v77, v233, v77, vcc
	v_cmp_lt_u32_e32 vcc, s50, v49
	v_add_u32_e32 v49, 0xfffffe95, v48
	s_nop 0
	v_cndmask_b32_e32 v45, v233, v45, vcc
	v_cmp_lt_u32_e32 vcc, s50, v49
	v_add_u32_e32 v49, 0xfffffeb5, v48
	s_nop 0
	v_cndmask_b32_e32 v78, v233, v78, vcc
	v_cmp_lt_u32_e32 vcc, s50, v49
	v_add_u32_e32 v49, 0xfffffe96, v48
	v_add_u32_e32 v48, 0xfffffeb6, v48
	v_cndmask_b32_e32 v46, v233, v46, vcc
	v_cmp_lt_u32_e32 vcc, s50, v49
	s_nop 1
	v_cndmask_b32_e32 v79, v233, v79, vcc
	v_cmp_lt_u32_e32 vcc, s50, v48
	s_nop 1
	v_cndmask_b32_e32 v47, v233, v47, vcc

.Latt_swa_norescale:
	v_exp_f32_e32 v64, v64
	v_exp_f32_e32 v65, v65
	v_exp_f32_e32 v66, v66
	v_exp_f32_e32 v67, v67
	v_exp_f32_e32 v68, v68
	v_exp_f32_e32 v69, v69
	v_exp_f32_e32 v70, v70
	v_exp_f32_e32 v71, v71
	v_cvt_pk_bf16_f32 v170, v64, v65
	v_cvt_pk_bf16_f32 v171, v66, v67
	v_cvt_pk_bf16_f32 v172, v68, v69
	v_cvt_pk_bf16_f32 v173, v70, v71
	s_waitcnt lgkmcnt(3)
	s_nop 0
	v_mfma_f32_32x32x16_bf16 v[0:15], v[210:213], v[170:173], v[0:15]
	ds_read_b128 v[210:213], v209 offset:27712
	v_exp_f32_e32 v72, v72
	v_exp_f32_e32 v73, v73
	v_exp_f32_e32 v74, v74
	v_exp_f32_e32 v75, v75
	v_cvt_pk_bf16_f32 v174, v72, v73
	v_exp_f32_e32 v76, v76
	v_exp_f32_e32 v77, v77
	v_cvt_pk_bf16_f32 v175, v74, v75
	s_waitcnt lgkmcnt(3)
	v_mfma_f32_32x32x16_bf16 v[16:31], v[214:217], v[170:173], v[16:31]
	ds_read_b128 v[214:217], v209 offset:32320
	v_exp_f32_e32 v78, v78
	v_exp_f32_e32 v79, v79
	v_cvt_pk_bf16_f32 v176, v76, v77
	v_cvt_pk_bf16_f32 v177, v78, v79
	v_add_f32_e32 v198, v64, v68
	v_add_f32_e32 v199, v65, v69
	v_add_f32_e32 v200, v66, v70
	v_add_f32_e32 v201, v67, v71
	s_waitcnt lgkmcnt(3)
	v_mfma_f32_32x32x16_bf16 v[0:15], v[218:221], v[174:177], v[0:15]
	ds_read_b128 v[218:221], v209 offset:27744
	v_exp_f32_e32 v32, v32
	v_exp_f32_e32 v33, v33
	v_exp_f32_e32 v34, v34
	v_exp_f32_e32 v35, v35
	v_cvt_pk_bf16_f32 v170, v32, v33
	v_exp_f32_e32 v36, v36
	v_exp_f32_e32 v37, v37
	v_cvt_pk_bf16_f32 v171, v34, v35
	v_exp_f32_e32 v38, v38
	v_exp_f32_e32 v39, v39
	s_waitcnt lgkmcnt(3)
	v_mfma_f32_32x32x16_bf16 v[16:31], v[222:225], v[174:177], v[16:31]
	ds_read_b128 v[222:225], v209 offset:32352
	v_cvt_pk_bf16_f32 v172, v36, v37
	v_cvt_pk_bf16_f32 v173, v38, v39
	v_add_f32_e32 v198, v198, v72
	v_add_f32_e32 v199, v199, v73
	v_add_f32_e32 v200, v200, v74
	v_add_f32_e32 v201, v201, v75
	v_add_f32_e32 v198, v198, v76
	v_add_f32_e32 v199, v199, v77
	v_add_f32_e32 v200, v200, v78
	v_add_f32_e32 v201, v201, v79
	s_waitcnt lgkmcnt(3)
	v_mfma_f32_32x32x16_bf16 v[0:15], v[210:213], v[170:173], v[0:15]
	v_exp_f32_e32 v40, v40
	v_exp_f32_e32 v41, v41
	v_exp_f32_e32 v42, v42
	v_exp_f32_e32 v43, v43
	v_cvt_pk_bf16_f32 v174, v40, v41
	v_exp_f32_e32 v44, v44
	v_exp_f32_e32 v45, v45
	v_cvt_pk_bf16_f32 v175, v42, v43
	v_exp_f32_e32 v46, v46
	v_exp_f32_e32 v47, v47
	s_waitcnt lgkmcnt(2)
	v_mfma_f32_32x32x16_bf16 v[16:31], v[214:217], v[170:173], v[16:31]
	v_cvt_pk_bf16_f32 v176, v44, v45
	v_cvt_pk_bf16_f32 v177, v46, v47
	v_add_f32_e32 v198, v198, v32
	v_add_f32_e32 v199, v199, v33
	v_add_f32_e32 v200, v200, v34
	v_add_f32_e32 v201, v201, v35
	v_add_f32_e32 v198, v198, v36
	v_add_f32_e32 v199, v199, v37
	v_add_f32_e32 v200, v200, v38
	v_add_f32_e32 v201, v201, v39
	s_waitcnt lgkmcnt(1)
	v_mfma_f32_32x32x16_bf16 v[0:15], v[218:221], v[174:177], v[0:15]
	v_add_f32_e32 v198, v198, v40
	v_add_f32_e32 v199, v199, v41
	v_add_f32_e32 v200, v200, v42
	v_add_f32_e32 v201, v201, v43
	s_waitcnt lgkmcnt(0)
	v_mfma_f32_32x32x16_bf16 v[16:31], v[222:225], v[174:177], v[16:31]
	v_add_f32_e32 v198, v198, v44
	v_add_f32_e32 v199, v199, v45
	v_add_f32_e32 v200, v200, v46
	v_add_f32_e32 v201, v201, v47
	v_add_f32_e32 v198, v198, v199
	v_add_f32_e32 v200, v200, v201
	v_add_f32_e32 v198, v198, v200
	v_add_f32_e32 v121, v121, v198

.LBB0_116:
	ds_read_b128 v[112:115], v242 offset:0
	ds_read_b128 v[116:119], v242 offset:4608
	ds_read_b128 v[120:123], v242 offset:32
	ds_read_b128 v[124:127], v242 offset:4640
	s_waitcnt lgkmcnt(3)
	v_mfma_f32_32x32x16_bf16 v[64:79], v[112:115], v[130:133], v[96:111]
	ds_read_b128 v[112:115], v242 offset:64
	s_waitcnt lgkmcnt(3)
	v_mfma_f32_32x32x16_bf16 v[80:95], v[116:119], v[130:133], v[96:111]
	ds_read_b128 v[116:119], v242 offset:4672
	s_waitcnt lgkmcnt(3)
	v_mfma_f32_32x32x16_bf16 v[64:79], v[120:123], v[134:137], v[64:79]
	ds_read_b128 v[120:123], v242 offset:96
	s_waitcnt lgkmcnt(3)
	v_mfma_f32_32x32x16_bf16 v[80:95], v[124:127], v[134:137], v[80:95]
	ds_read_b128 v[124:127], v242 offset:4704
	s_waitcnt lgkmcnt(3)
	v_mfma_f32_32x32x16_bf16 v[64:79], v[112:115], v[138:141], v[64:79]
	s_waitcnt lgkmcnt(2)
	v_mfma_f32_32x32x16_bf16 v[80:95], v[116:119], v[138:141], v[80:95]
	s_waitcnt lgkmcnt(1)
	v_mfma_f32_32x32x16_bf16 v[64:79], v[120:123], v[142:145], v[64:79]
	s_waitcnt lgkmcnt(0)
	v_mfma_f32_32x32x16_bf16 v[80:95], v[124:127], v[142:145], v[80:95]
	ds_read_b128 v[112:115], v243 offset:27648
	ds_read_b128 v[116:119], v243 offset:32256
	ds_read_b128 v[120:123], v243 offset:36864
	ds_read_b128 v[124:127], v243 offset:41472
	s_cmp_eq_u32 s52, 0
	s_cselect_b32 s31, 0xff7fffff, 0
	s_nop 4
	v_max3_f32 v226, v64, v65, v66
	v_max3_f32 v227, v67, v68, v69
	v_max3_f32 v226, v226, v70, v71
	v_max3_f32 v227, v227, v72, v73
	v_max3_f32 v226, v226, v74, v75
	v_max3_f32 v227, v227, v76, v77
	v_max3_f32 v226, v226, v78, v79
	v_max3_f32 v228, v80, v81, v82
	v_max3_f32 v229, v83, v84, v85
	v_max3_f32 v228, v228, v86, v87
	v_max3_f32 v229, v229, v88, v89
	v_max3_f32 v228, v228, v90, v91
	v_max3_f32 v229, v229, v92, v93
	v_max3_f32 v228, v228, v94, v95
	v_max3_f32 v226, v226, v227, v228
	v_max_f32_e32 v226, v226, v229
	v_cmp_lt_f32_e32 vcc, s58, v226
	s_cmp_eq_u32 s52, 0
	s_cbranch_scc1 .Latt_diff_rare
	s_cbranch_vccnz .Latt_diff_rare
.Latt_diff_norescale:
	v_exp_f32_e32 v64, v64
	v_exp_f32_e32 v65, v65
	v_exp_f32_e32 v66, v66
	v_exp_f32_e32 v67, v67
	v_exp_f32_e32 v68, v68
	v_exp_f32_e32 v69, v69
	v_exp_f32_e32 v70, v70
	v_exp_f32_e32 v71, v71
	v_cvt_pk_bf16_f32 v218, v64, v65
	v_cvt_pk_bf16_f32 v219, v66, v67
	v_cvt_pk_bf16_f32 v220, v68, v69
	v_cvt_pk_bf16_f32 v221, v70, v71
	s_waitcnt lgkmcnt(3)
	s_nop 0
	v_mfma_f32_32x32x16_bf16 v[0:15], v[112:115], v[218:221], v[0:15]
	ds_read_b128 v[112:115], v243 offset:27680
	v_exp_f32_e32 v72, v72
	v_exp_f32_e32 v73, v73
	v_exp_f32_e32 v74, v74
	v_exp_f32_e32 v75, v75
	s_waitcnt lgkmcnt(3)
	v_mfma_f32_32x32x16_bf16 v[48:63], v[116:119], v[218:221], v[48:63]
	ds_read_b128 v[116:119], v243 offset:32288
	v_cvt_pk_bf16_f32 v222, v72, v73
	v_exp_f32_e32 v76, v76
	v_exp_f32_e32 v77, v77
	v_cvt_pk_bf16_f32 v223, v74, v75
	s_waitcnt lgkmcnt(3)
	v_mfma_f32_32x32x16_bf16 v[32:47], v[120:123], v[218:221], v[32:47]
	ds_read_b128 v[120:123], v243 offset:36896
	v_exp_f32_e32 v78, v78
	v_exp_f32_e32 v79, v79
	v_cvt_pk_bf16_f32 v224, v76, v77
	v_cvt_pk_bf16_f32 v225, v78, v79
	s_waitcnt lgkmcnt(3)
	v_mfma_f32_32x32x16_bf16 v[16:31], v[124:127], v[218:221], v[16:31]
	ds_read_b128 v[124:127], v243 offset:41504
	v_add_f32_e32 v226, v64, v68
	v_add_f32_e32 v227, v65, v69
	v_add_f32_e32 v228, v66, v70
	v_add_f32_e32 v229, v67, v71
	s_waitcnt lgkmcnt(3)
	v_mfma_f32_32x32x16_bf16 v[0:15], v[112:115], v[222:225], v[0:15]
	ds_read_b128 v[112:115], v243 offset:27712
	v_exp_f32_e32 v80, v80
	v_exp_f32_e32 v81, v81
	v_exp_f32_e32 v82, v82
	v_exp_f32_e32 v83, v83
	v_cvt_pk_bf16_f32 v218, v80, v81
	s_waitcnt lgkmcnt(3)
	v_mfma_f32_32x32x16_bf16 v[48:63], v[116:119], v[222:225], v[48:63]
	ds_read_b128 v[116:119], v243 offset:32320
	v_exp_f32_e32 v84, v84
	v_exp_f32_e32 v85, v85
	v_cvt_pk_bf16_f32 v219, v82, v83
	v_exp_f32_e32 v86, v86
	v_exp_f32_e32 v87, v87
	s_waitcnt lgkmcnt(3)
	v_mfma_f32_32x32x16_bf16 v[32:47], v[120:123], v[222:225], v[32:47]
	ds_read_b128 v[120:123], v243 offset:36928
	v_cvt_pk_bf16_f32 v220, v84, v85
	v_cvt_pk_bf16_f32 v221, v86, v87
	v_add_f32_e32 v226, v226, v72
	v_add_f32_e32 v227, v227, v73
	v_add_f32_e32 v228, v228, v74
	s_waitcnt lgkmcnt(3)
	v_mfma_f32_32x32x16_bf16 v[16:31], v[124:127], v[222:225], v[16:31]
	ds_read_b128 v[124:127], v243 offset:41536
	v_add_f32_e32 v229, v229, v75
	v_add_f32_e32 v226, v226, v76
	v_add_f32_e32 v227, v227, v77
	v_add_f32_e32 v228, v228, v78
	v_add_f32_e32 v229, v229, v79
	s_waitcnt lgkmcnt(3)
	v_mfma_f32_32x32x16_bf16 v[0:15], v[112:115], v[218:221], v[0:15]
	ds_read_b128 v[112:115], v243 offset:27744
	v_exp_f32_e32 v88, v88
	v_exp_f32_e32 v89, v89
	v_exp_f32_e32 v90, v90
	v_exp_f32_e32 v91, v91
	v_cvt_pk_bf16_f32 v222, v88, v89
	s_waitcnt lgkmcnt(3)
	v_mfma_f32_32x32x16_bf16 v[48:63], v[116:119], v[218:221], v[48:63]
	ds_read_b128 v[116:119], v243 offset:32352
	v_exp_f32_e32 v92, v92
	v_exp_f32_e32 v93, v93
	v_cvt_pk_bf16_f32 v223, v90, v91
	v_exp_f32_e32 v94, v94
	v_exp_f32_e32 v95, v95
	s_waitcnt lgkmcnt(3)
	v_mfma_f32_32x32x16_bf16 v[32:47], v[120:123], v[218:221], v[32:47]
	ds_read_b128 v[120:123], v243 offset:36960
	v_cvt_pk_bf16_f32 v224, v92, v93
	v_cvt_pk_bf16_f32 v225, v94, v95
	v_add_f32_e32 v226, v226, v80
	v_add_f32_e32 v227, v227, v81
	v_add_f32_e32 v228, v228, v82
	s_waitcnt lgkmcnt(3)
	v_mfma_f32_32x32x16_bf16 v[16:31], v[124:127], v[218:221], v[16:31]
	ds_read_b128 v[124:127], v243 offset:41568
	v_add_f32_e32 v229, v229, v83
	v_add_f32_e32 v226, v226, v84
	v_add_f32_e32 v227, v227, v85
	v_add_f32_e32 v228, v228, v86
	v_add_f32_e32 v229, v229, v87
	s_waitcnt lgkmcnt(3)
	v_mfma_f32_32x32x16_bf16 v[0:15], v[112:115], v[222:225], v[0:15]
	v_add_f32_e32 v226, v226, v88
	v_add_f32_e32 v227, v227, v89
	s_waitcnt lgkmcnt(2)
	v_mfma_f32_32x32x16_bf16 v[48:63], v[116:119], v[222:225], v[48:63]
	v_add_f32_e32 v228, v228, v90
	v_add_f32_e32 v229, v229, v91
	s_waitcnt lgkmcnt(1)
	v_mfma_f32_32x32x16_bf16 v[32:47], v[120:123], v[222:225], v[32:47]
	v_add_f32_e32 v226, v226, v92
	v_add_f32_e32 v227, v227, v93
	s_waitcnt lgkmcnt(0)
	v_mfma_f32_32x32x16_bf16 v[16:31], v[124:127], v[222:225], v[16:31]
	v_add_f32_e32 v228, v228, v94
	v_add_f32_e32 v229, v229, v95
	v_add_f32_e32 v226, v226, v227
	v_add_f32_e32 v228, v228, v229
	v_add_f32_e32 v226, v226, v228
	v_add_f32_e32 v157, v157, v226
